# v11 + coalesced 8-rows-x-128B V gather in DSA sparse attention + early L2 write-back at barrier arrival
# speedup vs baseline: 1.0047x; 1.0007x over previous
; __device__ __forceinline__ unsigned xb_add(unsigned* p, unsigned v) { return __hip_atomic_fetch_add(p, v, __ATOMIC_RELAXED, __HIP_MEMORY_SCOPE_AGENT); }
; __device__ __forceinline__ void xcd_barrier(const XcdBarrier& b) {
;     ...
;     if (threadIdx.x == 0) {
;         unsigned* bar = b.bar;
;         __builtin_amdgcn_s_waitcnt(0);
;         unsigned nloc = b.st[0], nx = b.st[1];
;         if (nloc == 0u) { xcd_barrier_complete(bar, b.x, nloc, nx); b.st[0] = nloc; b.st[1] = nx; }
;         const unsigned old = xb_add(&bar[XB_XSUB(b.x)], 1u);
;         const unsigned gen = old / nloc;
;         if (old + 1u == (gen + 1u) * nloc) {
.LBB0_227:
	s_mov_b64 s[8:9], exec
	v_mbcnt_lo_u32_b32 v0, s8, 0
	v_mbcnt_hi_u32_b32 v0, s9, v0
	v_cmp_eq_u32_e32 vcc, 0, v0
	s_and_saveexec_b64 s[6:7], vcc
	s_cbranch_execz .LBB0_229
	s_bcnt1_i32_b64 s2, s[8:9]
	v_mov_b32_e32 v4, s2
	buffer_wbl2 sc1
	v_readlane_b32 s2, v252, 1
	v_readlane_b32 s3, v252, 2
	s_nop 4
	global_atomic_add v4, v1, v4, s[2:3] sc0

; #define LAS __attribute__((address_space(3)))
; __device__ __forceinline__ void kv_gather(KVRegs& r, const bf16_t* Pb, const LAS unsigned short* il, int s, int lane) {
;     const int li = lane & 15, g4 = lane >> 4;
;     const unsigned ra = il[32 * s + li], rb = il[32 * s + 16 + li], rv = il[32 * s + (lane >> 1)];
;     const bf16_t* k0 = Pb + (size_t)ra * NP_ + PC_KC + 8 * g4; const bf16_t* k1 = Pb + (size_t)rb * NP_ + PC_KC + 8 * g4;
;     r.ka[0] = *(const bf16x8*)k0; r.ka[1] = *(const bf16x8*)(k0 + 32); r.kb[0] = *(const bf16x8*)k1; r.kb[1] = *(const bf16x8*)(k1 + 32);
;     const bf16_t* vp = Pb + (size_t)rv * NP_ + PC_VC + (lane & 1) * 32;
; #pragma unroll
;     for (int i = 0; i < 4; ++i) r.v[i] = *(const u32x4*)(vp + 8 * i);
; }
; __device__ __forceinline__ void dsa_unit(int b, int blk, const bf16_t* P, bf16_t* OB, LAS unsigned char* lds, int wave, int tid_in) {
;     ...
;             const int qs = wave * 2 + qq;
;             const LAS unsigned short* il = (const LAS unsigned short*)(lds + C_IDX + qs * 512);
;             const int cnt = *(const LAS int*)(lds + C_CNT + qs * 4);
;             bf16x8 bq[2];
;             { const bf16_t* qp = P + (tok0 + t0 + qs) * NP_ + PC_QC + (col & 7) * 64 + 8 * g4; bq[0] = *(const bf16x8*)qp; bq[1] = *(const bf16x8*)(qp + 32);
;               if (col >= 8) { bq[0] = (bf16x8){0, 0, 0, 0, 0, 0, 0, 0}; bq[1] = bq[0]; } }
;             float m = -1e30f, l = 0.f; f32x4 o[4];
; #pragma unroll
;             for (int db = 0; db < 4; ++db) o[db] = (f32x4){0.f, 0.f, 0.f, 0.f};
;             const int s_hi = ((cnt + 31) >> 5) - 1;
;             KVRegs kv[2];
;             kv_gather(kv[0], Pb, il, 0, lane);
.LBB0_1165:
	v_readlane_b32 s0, v255, 32
	s_mulk_i32 s0, 0x1c00
	v_readlane_b32 s10, v253, 41
	v_lshlrev_b32_e32 v5, 5, v0
	v_lshlrev_b32_e32 v7, 6, v0
	s_add_u32 s4, s10, s0
	v_and_b32_e32 v6, 32, v5
	v_and_b32_e32 v8, 63, v0
	v_lshlrev_b32_e32 v8, 4, v8
	v_readlane_b32 s0, v252, 26
	s_waitcnt vmcnt(0)
	v_mov_b32_e32 v105, 0
	v_lshlrev_b32_e32 v7, 9, v135
	v_and_b32_e32 v5, 0x180, v5
	v_add_u32_e32 v104, s0, v8
	v_add3_u32 v106, s0, v7, v5
	v_readlane_b32 s0, v255, 8
	s_waitcnt lgkmcnt(0)
	s_barrier
	v_mov_b32_e32 v5, s0
	ds_read_b32 v101, v5
	v_readlane_b32 s11, v253, 42
	s_addc_u32 s5, s11, 0
	v_readlane_b32 s0, v255, 30
	s_add_u32 s2, s0, s37
	v_readlane_b32 s0, v255, 31
	s_addc_u32 s3, s0, 0
	s_waitcnt lgkmcnt(0)
	v_readfirstlane_b32 s0, v101
	v_lshlrev_b32_e32 v2, 6, v133
	v_lshrrev_b32_e32 v3, 1, v0
	s_add_i32 s0, s0, 31
	v_and_b32_e32 v2, 0x1c0, v2
	v_and_b32_e32 v4, 24, v3
	v_lshlrev_b32_e32 v100, 2, v135
	v_lshlrev_b32_e32 v0, 3, v0
	s_ashr_i32 s6, s0, 5
	v_cmp_lt_u32_e64 s[44:45], 7, v132
	v_and_b32_e32 v107, 24, v0
	s_mov_b32 s7, 0
	s_cmp_gt_i32 s6, 0
	v_lshrrev_b32_e32 v108, 2, v3
	v_lshlrev_b32_e32 v108, 1, v108
	v_lshlrev_b32_e32 v109, 1, v132
	v_and_b32_e32 v92, 56, v0
	v_lshlrev_b32_e32 v92, 1, v92
	v_lshlrev_b32_e32 v94, 1, v4
	v_lshlrev_b32_e32 v98, 1, v2
	v_lshlrev_b32_e32 v96, 1, v134
	v_or_b32_e32 v110, 32, v100
	s_cbranch_scc0 .LBB0_1179
	v_readlane_b32 s0, v252, 20
	v_mov_b32_e32 v93, v1
	s_movk_i32 s9, 0x1000
	v_add_u32_e32 v0, s0, v108
	v_add_u32_e32 v2, s0, v109
	ds_read_u16 v86, v0
	ds_read_u16 v87, v0 offset:16
	ds_read_u16 v91, v0 offset:32
	ds_read_u16 v90, v0 offset:48
	ds_read_u16 v3, v2 offset:32
	ds_read_u16 v16, v2
	s_mov_b64 s[0:1], 0x1b00
	v_mov_b32_e32 v95, v1
	s_waitcnt lgkmcnt(2)
	s_nop 0
	v_lshl_add_u64 v[4:5], s[4:5], 0, v[92:93]
	s_waitcnt lgkmcnt(1)
	v_mul_u32_u24_e32 v2, 0x1c00, v3
	v_lshl_add_u64 v[4:5], v[4:5], 0, s[0:1]
	v_mov_b32_e32 v3, v1
	v_mad_u64_u32 v[52:53], s[98:99], v91, s21, v[4:5]
	v_mad_u64_u32 v[56:57], s[98:99], v87, s21, v[4:5]
	v_mad_u64_u32 v[84:85], s[98:99], v86, s21, v[4:5]
	v_mad_u64_u32 v[88:89], s[98:99], v90, s21, v[4:5]
	s_nop 0
	v_lshl_add_u64 v[2:3], s[4:5], 0, v[2:3]
	s_mul_i32 s0, s3, 0x1c00
	s_mul_hi_u32 s1, s2, 0x1c00
	s_add_i32 s8, s6, -1
	s_nop 0
	v_lshl_add_u64 v[2:3], v[2:3], 0, v[94:95]
	s_mov_b64 s[12:13], 0x1500
	s_add_i32 s1, s1, s0
	s_mul_i32 s0, s2, 0x1c00
	v_lshl_add_u64 v[4:5], v[2:3], 0, s[12:13]
	v_add_co_u32_e32 v2, vcc, s9, v2
	s_add_u32 s10, s10, s0
	s_nop 0
	v_addc_co_u32_e32 v3, vcc, 0, v3, vcc
	s_addc_u32 s11, s11, s1
	v_mov_b32_e32 v99, v1
	global_load_dwordx4 v[52:55], v[52:53], off
	global_load_dwordx4 v[56:59], v[56:57], off
	global_load_dwordx4 v[60:63], v[4:5], off offset:64
	global_load_dwordx4 v[64:67], v[2:3], off offset:1280
	v_lshl_add_u64 v[2:3], s[10:11], 0, v[98:99]
	v_mov_b32_e32 v97, v1
	v_lshl_add_u64 v[2:3], v[2:3], 0, v[96:97]
	global_load_dwordx4 v[4:7], v[2:3], off offset:3136
	global_load_dwordx4 v[8:11], v[2:3], off offset:3072
	v_mov_b64_e32 v[2:3], s[4:5]
	s_waitcnt lgkmcnt(0)
	v_mad_u64_u32 v[2:3], s[10:11], v16, s21, v[2:3]
	v_lshl_add_u64 v[2:3], v[2:3], 0, v[94:95]
	v_lshl_add_u64 v[16:17], v[2:3], 0, s[12:13]
	v_add_co_u32_e32 v2, vcc, s9, v2
	v_mov_b32_e32 v0, v1
	s_nop 0
	v_addc_co_u32_e32 v3, vcc, 0, v3, vcc
	global_load_dwordx4 v[80:83], v[16:17], off offset:64
	global_load_dwordx4 v[76:79], v[2:3], off offset:1280
	global_load_dwordx4 v[84:87], v[84:85], off
	global_load_dwordx4 v[88:91], v[88:89], off
	v_mov_b32_e32 v2, v1
	v_mov_b32_e32 v3, v1
	v_mov_b64_e32 v[38:39], v[2:3]
	v_mov_b64_e32 v[42:43], v[2:3]
	v_mov_b64_e32 v[46:47], v[2:3]
	v_mov_b64_e32 v[50:51], v[2:3]
	v_readlane_b32 s24, v250, 5
	v_readlane_b32 s22, v255, 27
	v_or_b32_e32 v99, 32, v100
	v_mov_b32_e32 v102, 0xf149f2ca
	v_mov_b32_e32 v97, 0
	v_readlane_b32 s9, v255, 3
	v_mov_b64_e32 v[36:37], v[0:1]
	v_mov_b64_e32 v[40:41], v[0:1]
	v_mov_b64_e32 v[44:45], v[0:1]
	v_mov_b64_e32 v[48:49], v[0:1]
	v_readlane_b32 s25, v250, 6
	v_readlane_b32 s30, v250, 11
	v_readlane_b32 s31, v250, 12
	v_readlane_b32 s23, v255, 28
	v_readlane_b32 s26, v250, 7
	v_readlane_b32 s27, v250, 8
	v_readlane_b32 s28, v250, 9
	v_readlane_b32 s29, v250, 10
	s_waitcnt vmcnt(5)
	v_cndmask_b32_e64 v75, v7, 0, s[44:45]
	s_waitcnt vmcnt(4)
	v_cndmask_b32_e64 v71, v11, 0, s[44:45]
	v_cndmask_b32_e64 v70, v10, 0, s[44:45]
	v_cndmask_b32_e64 v69, v9, 0, s[44:45]
	v_cndmask_b32_e64 v68, v8, 0, s[44:45]
	v_cndmask_b32_e64 v74, v6, 0, s[44:45]
	v_cndmask_b32_e64 v73, v5, 0, s[44:45]
	v_cndmask_b32_e64 v72, v4, 0, s[44:45]
	s_branch .LBB0_1169

; #define LAS __attribute__((address_space(3)))
; __device__ __forceinline__ void kv_gather(KVRegs& r, const bf16_t* Pb, const LAS unsigned short* il, int s, int lane) {
;     const int li = lane & 15, g4 = lane >> 4;
;     const unsigned ra = il[32 * s + li], rb = il[32 * s + 16 + li], rv = il[32 * s + (lane >> 1)];
;     const bf16_t* k0 = Pb + (size_t)ra * NP_ + PC_KC + 8 * g4; const bf16_t* k1 = Pb + (size_t)rb * NP_ + PC_KC + 8 * g4;
;     r.ka[0] = *(const bf16x8*)k0; r.ka[1] = *(const bf16x8*)(k0 + 32); r.kb[0] = *(const bf16x8*)k1; r.kb[1] = *(const bf16x8*)(k1 + 32);
;     const bf16_t* vp = Pb + (size_t)rv * NP_ + PC_VC + (lane & 1) * 32;
; #pragma unroll
;     for (int i = 0; i < 4; ++i) r.v[i] = *(const u32x4*)(vp + 8 * i);
; }
; __device__ __forceinline__ void dsa_unit(int b, int blk, const bf16_t* P, bf16_t* OB, LAS unsigned char* lds, int wave, int tid_in) {
;     ...
;             for (int s = 0; s <= s_hi; s += 2) {
; #pragma unroll
;                 for (int j = 0; j < 2; ++j) {
;                     if (s + j <= s_hi) {
;                         if (s + j + 1 <= s_hi) kv_gather(kv[(j + 1) % 2], Pb, il, s + j + 1, lane);
;                         attn_step(kv[j], bq, vl, lane, CountMask{32 * (s + j), cnt}, m, l, o);
.LBB0_1169:
	s_cmp_lt_i32 s7, s8
	s_cbranch_scc0 .LBB0_1171
	v_add_u32_e32 v0, s9, v109
	v_add_u32_e32 v2, 0x10140, v0
	v_add_u32_e32 v0, 0x10160, v0
	ds_read_u16 v2, v2
	ds_read_u16 v3, v0
	v_add_u32_e32 v0, s9, v108
	v_add_u32_e32 v0, 0x10140, v0
	ds_read_u16 v22, v0
	ds_read_u16 v34, v0 offset:16
	ds_read_u16 v30, v0 offset:32
	ds_read_u16 v26, v0 offset:48
	s_waitcnt lgkmcnt(2)
	v_mul_u32_u24_e32 v0, 0x1c00, v2
	s_waitcnt lgkmcnt(1)
	v_mul_u32_u24_e32 v2, 0x1c00, v3
	v_mov_b32_e32 v3, v1
	v_lshl_add_u64 v[4:5], s[4:5], 0, v[0:1]
	v_mov_b32_e32 v95, v1
	v_lshl_add_u64 v[2:3], s[4:5], 0, v[2:3]
	v_lshl_add_u64 v[4:5], v[4:5], 0, v[94:95]
	s_mov_b64 s[0:1], 0x1500
	v_lshl_add_u64 v[2:3], v[2:3], 0, v[94:95]
	v_lshl_add_u64 v[12:13], v[4:5], 0, s[0:1]
	v_lshl_add_u64 v[16:17], v[2:3], 0, s[0:1]
	s_movk_i32 s0, 0x1000
	v_add_co_u32_e32 v4, vcc, s0, v4
	v_mov_b32_e32 v93, v1
	s_nop 0
	v_addc_co_u32_e32 v5, vcc, 0, v5, vcc
	v_add_co_u32_e32 v2, vcc, s0, v2
	s_mov_b64 s[0:1], 0x1b00
	s_nop 0
	v_addc_co_u32_e32 v3, vcc, 0, v3, vcc
	global_load_dwordx4 v[4:7], v[4:5], off offset:1280
	s_nop 0
	global_load_dwordx4 v[8:11], v[2:3], off offset:1280
	s_nop 0
	global_load_dwordx4 v[12:15], v[12:13], off offset:64
	s_nop 0
	global_load_dwordx4 v[16:19], v[16:17], off offset:64
	v_mov_b64_e32 v[2:3], s[4:5]
	v_lshl_add_u64 v[2:3], v[2:3], 0, v[92:93]
	v_lshl_add_u64 v[2:3], v[2:3], 0, s[0:1]
	s_waitcnt lgkmcnt(0)
	v_mad_u64_u32 v[20:21], s[98:99], v22, s21, v[2:3]
	v_mad_u64_u32 v[24:25], s[98:99], v26, s21, v[2:3]
	v_mad_u64_u32 v[28:29], s[98:99], v30, s21, v[2:3]
	v_mad_u64_u32 v[32:33], s[98:99], v34, s21, v[2:3]
	global_load_dwordx4 v[20:23], v[20:21], off
	global_load_dwordx4 v[24:27], v[24:25], off
	global_load_dwordx4 v[28:31], v[28:29], off
	global_load_dwordx4 v[32:35], v[32:33], off
	s_waitcnt vmcnt(10)
	v_mfma_f32_16x16x32_bf16 v[112:115], v[76:79], v[68:71], 0
	v_subrev_u32_e32 v0, 32, v99
	v_cmp_lt_i32_e32 vcc, v0, v101
	v_add_u32_e32 v0, -16, v99
	v_mfma_f32_16x16x32_bf16 v[118:121], v[64:67], v[68:71], 0
	v_add_u32_e32 v3, v104, v105
	s_waitcnt vmcnt(9)
	ds_write_b128 v3, v[84:87]
	s_waitcnt vmcnt(8)
	ds_write_b128 v3, v[56:59] offset:1024
	ds_write_b128 v3, v[52:55] offset:2048
	s_waitcnt vmcnt(8)
	ds_write_b128 v3, v[88:91] offset:3072
	s_branch .Ldsa3_tailA_0
.LBB0_1171:
	s_waitcnt vmcnt(2)
	v_mfma_f32_16x16x32_bf16 v[112:115], v[76:79], v[68:71], 0
	v_subrev_u32_e32 v0, 32, v99
	v_cmp_lt_i32_e32 vcc, v0, v101
	v_add_u32_e32 v0, -16, v99
	v_mfma_f32_16x16x32_bf16 v[118:121], v[64:67], v[68:71], 0
	v_add_u32_e32 v3, v104, v105
	s_waitcnt vmcnt(1)
	ds_write_b128 v3, v[84:87]
	s_waitcnt vmcnt(0)
	ds_write_b128 v3, v[56:59] offset:1024
	ds_write_b128 v3, v[52:55] offset:2048
	s_waitcnt vmcnt(0)
	ds_write_b128 v3, v[88:91] offset:3072

; #define LAS __attribute__((address_space(3)))
; __device__ __forceinline__ unsigned cvt_pk_bf16(float lo, float hi) { const f32x2 v = {lo, hi}; const bf16x2_t b = __builtin_convertvector(v, bf16x2_t); return __builtin_bit_cast(unsigned, b); }
; __device__ __forceinline__ float fast_exp2(float x) { return __builtin_amdgcn_exp2f(x); }
; #define MFMA16(a, b, c) __builtin_amdgcn_mfma_f32_16x16x32_bf16((a), (b), (c), 0, 0, 0)
; __device__ __forceinline__ s16x4 tr_read(LAS unsigned char* p) { return __builtin_bit_cast(s16x4, __builtin_amdgcn_ds_read_tr16_b64_v4i16((LAS v4i16_t*)p)); }
; template <class MaskF>
; __device__ __forceinline__ void attn_step(const KVRegs& r, const bf16x8 (&bq)[2], LAS unsigned char* vl, int lane, const MaskF mask, float& m, float& l, f32x4 (&o)[4]) {
;     ...
;     float p[8], ps = 0.f;
; #pragma unroll
;     for (int e = 0; e < 8; ++e) { p[e] = fast_exp2(x[e] - mn); ps += p[e]; }
;     l += ps;
;     u32x4 pw; pw.x = cvt_pk_bf16(p[0], p[1]); pw.y = cvt_pk_bf16(p[2], p[3]); pw.z = cvt_pk_bf16(p[4], p[5]); pw.w = cvt_pk_bf16(p[6], p[7]);
;     const bf16x8 pf = __builtin_bit_cast(bf16x8, pw);
;     asm volatile("s_waitcnt lgkmcnt(0)" ::: "memory");
;     LAS unsigned char* rd = vl + (4 * g4 + ((lane & 15) >> 2)) * 128 + (lane & 3) * 8;
; #pragma unroll
;     for (int db = 0; db < 4; ++db) { const s16x4 t0 = tr_read(rd + db * 32), t1 = tr_read(rd + 16 * 128 + db * 32);
;         const bf16x8 vf = (bf16x8){t0[0], t0[1], t0[2], t0[3], t1[0], t1[1], t1[2], t1[3]};
;         o[db] = MFMA16(vf, pf, o[db]); }
;     asm volatile("s_waitcnt lgkmcnt(0)" ::: "memory");
; __device__ __forceinline__ void kv_gather(KVRegs& r, const bf16_t* Pb, const LAS unsigned short* il, int s, int lane) {
;     const int li = lane & 15, g4 = lane >> 4;
;     const unsigned ra = il[32 * s + li], rb = il[32 * s + 16 + li], rv = il[32 * s + (lane >> 1)];
;     const bf16_t* k0 = Pb + (size_t)ra * NP_ + PC_KC + 8 * g4; const bf16_t* k1 = Pb + (size_t)rb * NP_ + PC_KC + 8 * g4;
;     r.ka[0] = *(const bf16x8*)k0; r.ka[1] = *(const bf16x8*)(k0 + 32); r.kb[0] = *(const bf16x8*)k1; r.kb[1] = *(const bf16x8*)(k1 + 32);
;     const bf16_t* vp = Pb + (size_t)rv * NP_ + PC_VC + (lane & 1) * 32;
; #pragma unroll
;     for (int i = 0; i < 4; ++i) r.v[i] = *(const u32x4*)(vp + 8 * i);
; }
.LBB0_1173:
	v_sub_f32_e32 v102, v112, v103
	v_exp_f32_e32 v102, v102
	v_sub_f32_e32 v114, v114, v103
	v_exp_f32_e32 v114, v114
	v_sub_f32_e32 v113, v113, v103
	v_exp_f32_e32 v113, v113
	v_sub_f32_e32 v111, v111, v103
	v_exp_f32_e32 v111, v111
	v_sub_f32_e32 v95, v95, v103
	v_add_f32_e32 v112, 0, v102
	v_exp_f32_e32 v95, v95
	v_sub_f32_e32 v93, v93, v103
	v_add_f32_e32 v112, v114, v112
	v_exp_f32_e32 v93, v93
	v_sub_f32_e32 v2, v2, v103
	v_sub_f32_e32 v0, v0, v103
	v_add_f32_e32 v112, v113, v112
	v_exp_f32_e32 v2, v2
	v_exp_f32_e32 v0, v0
	v_add_f32_e32 v112, v111, v112
	v_add_f32_e32 v112, v95, v112
	v_add_f32_e32 v112, v93, v112
	v_add_f32_e32 v112, v2, v112
	v_cvt_pk_bf16_f32 v115, v2, v0
	s_waitcnt lgkmcnt(0)
	v_add_u32_e32 v2, v106, v107
	ds_read_b64_tr_b16 v[118:119], v2 offset:2048
	ds_read_b64_tr_b16 v[116:117], v2
	ds_read_b64_tr_b16 v[120:121], v2 offset:32
	v_add_f32_e32 v112, v0, v112
	v_add_f32_e32 v97, v112, v97
	v_cvt_pk_bf16_f32 v112, v102, v114
	v_cvt_pk_bf16_f32 v113, v113, v111
	v_cvt_pk_bf16_f32 v114, v95, v93
	ds_read_b64_tr_b16 v[122:123], v2 offset:2080
	s_add_i32 s0, s7, 1
	s_waitcnt lgkmcnt(2)
	v_mfma_f32_16x16x32_bf16 v[48:51], v[116:119], v[112:115], v[48:51]
	ds_read_b64_tr_b16 v[116:117], v2 offset:64
	ds_read_b64_tr_b16 v[118:119], v2 offset:2112
	s_cmp_ge_i32 s0, s6
	s_waitcnt lgkmcnt(0)
	v_mfma_f32_16x16x32_bf16 v[40:43], v[116:119], v[112:115], v[40:43]
	ds_read_b64_tr_b16 v[116:117], v2 offset:96
	ds_read_b64_tr_b16 v[118:119], v2 offset:2144
	s_waitcnt lgkmcnt(0)
	v_mfma_f32_16x16x32_bf16 v[44:47], v[120:123], v[112:115], v[44:47]
	s_waitcnt lgkmcnt(0)
	v_mfma_f32_16x16x32_bf16 v[36:39], v[116:119], v[112:115], v[36:39]
	s_cbranch_scc1 .LBB0_1167
	s_cmp_ge_i32 s0, s8
	s_cbranch_scc1 .LBB0_1176
	v_add_u32_e32 v0, s9, v109
	v_add_u32_e32 v52, 0x10180, v0
	v_add_u32_e32 v0, 0x101a0, v0
	ds_read_u16 v52, v52
	ds_read_u16 v53, v0
	v_add_u32_e32 v0, s9, v108
	v_add_u32_e32 v0, 0x10180, v0
	ds_read_u16 v86, v0
	ds_read_u16 v87, v0 offset:16
	ds_read_u16 v91, v0 offset:32
	ds_read_u16 v90, v0 offset:48
	s_waitcnt lgkmcnt(2)
	v_mul_u32_u24_e32 v0, 0x1c00, v52
	s_waitcnt lgkmcnt(1)
	v_mul_u32_u24_e32 v52, 0x1c00, v53
	v_mov_b32_e32 v53, v1
	v_lshl_add_u64 v[54:55], s[4:5], 0, v[0:1]
	v_mov_b32_e32 v95, v1
	v_lshl_add_u64 v[52:53], s[4:5], 0, v[52:53]
	v_lshl_add_u64 v[54:55], v[54:55], 0, v[94:95]
	s_mov_b64 s[0:1], 0x1500
	v_lshl_add_u64 v[52:53], v[52:53], 0, v[94:95]
	v_lshl_add_u64 v[56:57], v[54:55], 0, s[0:1]
	v_lshl_add_u64 v[58:59], v[52:53], 0, s[0:1]
	s_movk_i32 s0, 0x1000
	v_add_co_u32_e32 v54, vcc, s0, v54
	v_mov_b32_e32 v93, v1
	s_nop 0
	v_addc_co_u32_e32 v55, vcc, 0, v55, vcc
	v_add_co_u32_e32 v52, vcc, s0, v52
	s_nop 1
	v_addc_co_u32_e32 v53, vcc, 0, v53, vcc
	global_load_dwordx4 v[76:79], v[54:55], off offset:1280
	global_load_dwordx4 v[64:67], v[52:53], off offset:1280
	global_load_dwordx4 v[80:83], v[56:57], off offset:64
	global_load_dwordx4 v[60:63], v[58:59], off offset:64
	v_mov_b64_e32 v[54:55], s[4:5]
	v_lshl_add_u64 v[54:55], v[54:55], 0, v[92:93]
	s_mov_b64 s[10:11], 0x1b00
	v_lshl_add_u64 v[54:55], v[54:55], 0, s[10:11]
	s_waitcnt lgkmcnt(0)
	v_mad_u64_u32 v[84:85], s[98:99], v86, s21, v[54:55]
	v_mad_u64_u32 v[88:89], s[98:99], v90, s21, v[54:55]
	v_mad_u64_u32 v[52:53], s[98:99], v91, s21, v[54:55]
	v_mad_u64_u32 v[56:57], s[98:99], v87, s21, v[54:55]
	global_load_dwordx4 v[84:87], v[84:85], off
	global_load_dwordx4 v[88:91], v[88:89], off
	global_load_dwordx4 v[52:55], v[52:53], off
	global_load_dwordx4 v[56:59], v[56:57], off
	s_waitcnt vmcnt(8)
	s_branch .Ldsa3_bodyB_0

; #define LAS __attribute__((address_space(3)))
; __device__ __forceinline__ float fast_exp2(float x) { return __builtin_amdgcn_exp2f(x); }
; __device__ __forceinline__ float xmax16(float v) { const auto r = __builtin_amdgcn_permlane16_swap(__float_as_uint(v), __float_as_uint(v), false, false); return fmaxf(__uint_as_float(r[0]), __uint_as_float(r[1])); }
; __device__ __forceinline__ float xmax32(float v) { const auto r = __builtin_amdgcn_permlane32_swap(__float_as_uint(v), __float_as_uint(v), false, false); return fmaxf(__uint_as_float(r[0]), __uint_as_float(r[1])); }
; #define MFMA16(a, b, c) __builtin_amdgcn_mfma_f32_16x16x32_bf16((a), (b), (c), 0, 0, 0)
; template <class MaskF>
; __device__ __forceinline__ void attn_step(const KVRegs& r, const bf16x8 (&bq)[2], LAS unsigned char* vl, int lane, const MaskF mask, float& m, float& l, f32x4 (&o)[4]) {
;     ...
;     { LAS unsigned char* wp = vl + (lane >> 1) * 128 + (lane & 1) * 64;
; #pragma unroll
;       for (int i = 0; i < 4; ++i) *(LAS u32x4*)(wp + 16 * i) = r.v[i]; }
;     f32x4 sa = (f32x4){0.f, 0.f, 0.f, 0.f}, sb = (f32x4){0.f, 0.f, 0.f, 0.f};
;     sa = MFMA16(r.ka[0], bq[0], sa); sa = MFMA16(r.ka[1], bq[1], sa);
;     sb = MFMA16(r.kb[0], bq[0], sb); sb = MFMA16(r.kb[1], bq[1], sb);
;     float x[8];
; #pragma unroll
;     for (int e = 0; e < 4; ++e) { x[e] = mask(4 * g4 + e, sa[e]); x[4 + e] = mask(16 + 4 * g4 + e, sb[e]); }
;     float tm = fmaxf(fmaxf(fmaxf(x[0], x[1]), fmaxf(x[2], x[3])), fmaxf(fmaxf(x[4], x[5]), fmaxf(x[6], x[7])));
;     tm = xmax32(xmax16(tm));
;     const float mn = fmaxf(m, tm);
;     if (__ballot(mn > m)) { const float al = fast_exp2(m - mn); l *= al;
; #pragma unroll
;         for (int db = 0; db < 4; ++db) o[db] = o[db] * al; }
.Ldsa3_bodyB_0:
	v_mfma_f32_16x16x32_bf16 v[112:115], v[4:7], v[68:71], 0
	v_cmp_lt_i32_e32 vcc, v99, v101
	v_add_u32_e32 v0, 16, v99
	ds_write_b128 v3, v[20:23]
	v_mfma_f32_16x16x32_bf16 v[118:121], v[8:11], v[68:71], 0
	ds_write_b128 v3, v[32:35] offset:1024
	ds_write_b128 v3, v[28:31] offset:2048
	ds_write_b128 v3, v[24:27] offset:3072
	v_mfma_f32_16x16x32_bf16 v[114:117], v[12:15], v[72:75], v[112:115]
	v_mfma_f32_16x16x32_bf16 v[118:121], v[16:19], v[72:75], v[118:121]
	s_nop 6
	v_cndmask_b32_e32 v112, v233, v114, vcc
	v_cmp_lt_i32_e32 vcc, v0, v101
	v_add_u32_e32 v0, 1, v99
	s_nop 0
	v_cndmask_b32_e32 v95, v233, v118, vcc
	v_cmp_lt_i32_e32 vcc, v0, v101
	v_add_u32_e32 v0, 17, v99
	s_nop 0
	v_cndmask_b32_e32 v114, v233, v115, vcc
	v_cmp_lt_i32_e32 vcc, v0, v101
	v_add_u32_e32 v0, 2, v99
	v_max_f32_e32 v102, v114, v114
	v_cndmask_b32_e32 v93, v233, v119, vcc
	v_cmp_lt_i32_e32 vcc, v0, v101
	v_add_u32_e32 v0, 18, v99
	v_max_f32_e32 v115, v112, v112
	v_cndmask_b32_e32 v113, v233, v116, vcc
	v_cmp_lt_i32_e32 vcc, v0, v101
	v_add_u32_e32 v0, 3, v99
	v_max_f32_e32 v102, v115, v102
	v_cndmask_b32_e32 v3, v233, v120, vcc
	v_cmp_lt_i32_e32 vcc, v0, v101
	v_add_u32_e32 v0, 19, v99
	v_max_f32_e32 v116, v113, v113
	v_cndmask_b32_e32 v111, v233, v117, vcc
	v_cmp_lt_i32_e32 vcc, v0, v101
	v_max_f32_e32 v115, v111, v111
	v_max_f32_e32 v115, v116, v115
	v_cndmask_b32_e32 v0, v233, v121, vcc
	v_max_f32_e32 v116, v0, v0
	v_max_f32_e32 v117, v3, v3
	v_max_f32_e32 v116, v117, v116
	v_max3_f32 v116, v95, v93, v116
	v_max3_f32 v102, v102, v115, v116
	v_mov_b32_e32 v115, v102
	s_nop 1
	v_permlane16_swap_b32_e32 v102, v115
	v_max_f32_e32 v115, v115, v115
	v_max_f32_e32 v102, v102, v102
	v_max_f32_e32 v102, v102, v115
	v_mov_b32_e32 v115, v102
	s_nop 1
	v_permlane32_swap_b32_e32 v102, v115
	v_max3_f32 v102, v103, v102, v115
	v_cmp_gt_f32_e32 vcc, v102, v103
	s_cbranch_vccz .LBB0_1178
	v_sub_f32_e32 v103, v103, v102
	v_exp_f32_e32 v116, v103
	s_nop 0
	v_mul_f32_e32 v97, v97, v116
	v_pk_mul_f32 v[50:51], v[50:51], v[116:117] op_sel_hi:[1,0]
	v_pk_mul_f32 v[48:49], v[48:49], v[116:117] op_sel_hi:[1,0]
	v_pk_mul_f32 v[46:47], v[46:47], v[116:117] op_sel_hi:[1,0]
	v_pk_mul_f32 v[44:45], v[44:45], v[116:117] op_sel_hi:[1,0]
	v_pk_mul_f32 v[42:43], v[42:43], v[116:117] op_sel_hi:[1,0]
	v_pk_mul_f32 v[40:41], v[40:41], v[116:117] op_sel_hi:[1,0]
	v_pk_mul_f32 v[38:39], v[38:39], v[116:117] op_sel_hi:[1,0]
	v_pk_mul_f32 v[36:37], v[36:37], v[116:117] op_sel_hi:[1,0]

; #define LAS __attribute__((address_space(3)))
; __device__ __forceinline__ void kv_gather(KVRegs& r, const bf16_t* Pb, const LAS unsigned short* il, int s, int lane) {
;     const int li = lane & 15, g4 = lane >> 4;
;     const unsigned ra = il[32 * s + li], rb = il[32 * s + 16 + li], rv = il[32 * s + (lane >> 1)];
;     const bf16_t* k0 = Pb + (size_t)ra * NP_ + PC_KC + 8 * g4; const bf16_t* k1 = Pb + (size_t)rb * NP_ + PC_KC + 8 * g4;
;     r.ka[0] = *(const bf16x8*)k0; r.ka[1] = *(const bf16x8*)(k0 + 32); r.kb[0] = *(const bf16x8*)k1; r.kb[1] = *(const bf16x8*)(k1 + 32);
;     const bf16_t* vp = Pb + (size_t)rv * NP_ + PC_VC + (lane & 1) * 32;
; #pragma unroll
;     for (int i = 0; i < 4; ++i) r.v[i] = *(const u32x4*)(vp + 8 * i);
; }
; __device__ __forceinline__ void dsa_unit(int b, int blk, const bf16_t* P, bf16_t* OB, LAS unsigned char* lds, int wave, int tid_in) {
;     ...
;             const int qs = wave * 2 + qq;
;             const LAS unsigned short* il = (const LAS unsigned short*)(lds + C_IDX + qs * 512);
;             const int cnt = *(const LAS int*)(lds + C_CNT + qs * 4);
;             bf16x8 bq[2];
;             { const bf16_t* qp = P + (tok0 + t0 + qs) * NP_ + PC_QC + (col & 7) * 64 + 8 * g4; bq[0] = *(const bf16x8*)qp; bq[1] = *(const bf16x8*)(qp + 32);
;               if (col >= 8) { bq[0] = (bf16x8){0, 0, 0, 0, 0, 0, 0, 0}; bq[1] = bq[0]; } }
;             float m = -1e30f, l = 0.f; f32x4 o[4];
; #pragma unroll
;             for (int db = 0; db < 4; ++db) o[db] = (f32x4){0.f, 0.f, 0.f, 0.f};
;             const int s_hi = ((cnt + 31) >> 5) - 1;
;             KVRegs kv[2];
;             kv_gather(kv[0], Pb, il, 0, lane);
.LBB0_1182:
	s_or_b64 exec, exec, s[6:7]
	v_readlane_b32 s0, v255, 9
	v_readlane_b32 s1, v255, 30
	s_nop 0
	v_mov_b32_e32 v0, s0
	ds_read_b32 v101, v0
	v_readlane_b32 s0, v252, 27
	s_add_u32 s2, s1, s0
	v_readlane_b32 s0, v255, 31
	s_addc_u32 s3, s0, 0
	s_waitcnt lgkmcnt(0)
	v_readfirstlane_b32 s0, v101
	s_add_i32 s0, s0, 31
	s_ashr_i32 s6, s0, 5
	s_cmp_lt_i32 s6, 1
	s_cbranch_scc1 .LBB0_1196
	v_readlane_b32 s0, v252, 19
	v_mov_b32_e32 v93, v1
	s_movk_i32 s10, 0x1000
	v_add_u32_e32 v0, s0, v108
	v_add_u32_e32 v2, s0, v109
	ds_read_u16 v86, v0
	ds_read_u16 v87, v0 offset:16
	ds_read_u16 v91, v0 offset:32
	ds_read_u16 v90, v0 offset:48
	ds_read_u16 v3, v2 offset:32
	s_waitcnt vmcnt(6)
	ds_read_u16 v64, v2
	s_mov_b64 s[0:1], 0x1b00
	v_mov_b32_e32 v95, v1
	s_waitcnt lgkmcnt(2)
	s_nop 0
	v_lshl_add_u64 v[36:37], s[4:5], 0, v[92:93]
	s_waitcnt lgkmcnt(1)
	v_mul_u32_u24_e32 v2, 0x1c00, v3
	v_lshl_add_u64 v[36:37], v[36:37], 0, s[0:1]
	v_mov_b32_e32 v3, v1
	s_waitcnt vmcnt(1)
	v_mad_u64_u32 v[44:45], s[98:99], v91, s21, v[36:37]
	v_mad_u64_u32 v[48:49], s[98:99], v87, s21, v[36:37]
	v_mad_u64_u32 v[84:85], s[98:99], v86, s21, v[36:37]
	v_mad_u64_u32 v[88:89], s[98:99], v90, s21, v[36:37]
	s_nop 0
	v_lshl_add_u64 v[2:3], s[4:5], 0, v[2:3]
	s_mul_i32 s0, s3, 0x1c00
	s_mul_hi_u32 s1, s2, 0x1c00
	s_add_i32 s7, s6, -1
	s_nop 0
	v_lshl_add_u64 v[2:3], v[2:3], 0, v[94:95]
	s_mov_b64 s[12:13], 0x1500
	s_add_i32 s1, s1, s0
	s_mul_i32 s0, s2, 0x1c00
	v_readlane_b32 s8, v253, 41
	v_lshl_add_u64 v[36:37], v[2:3], 0, s[12:13]
	v_add_co_u32_e32 v2, vcc, s10, v2
	v_readlane_b32 s9, v253, 42
	s_add_u32 s8, s8, s0
	v_addc_co_u32_e32 v3, vcc, 0, v3, vcc
	s_addc_u32 s9, s9, s1
	v_mov_b32_e32 v99, v1
	global_load_dwordx4 v[44:47], v[44:45], off
	global_load_dwordx4 v[48:51], v[48:49], off
	global_load_dwordx4 v[56:59], v[36:37], off offset:64
	global_load_dwordx4 v[60:63], v[2:3], off offset:1280
	v_lshl_add_u64 v[2:3], s[8:9], 0, v[98:99]
	v_mov_b32_e32 v97, v1
	v_lshl_add_u64 v[2:3], v[2:3], 0, v[96:97]
	global_load_dwordx4 v[36:39], v[2:3], off offset:3136
	global_load_dwordx4 v[40:43], v[2:3], off offset:3072
	v_mov_b64_e32 v[2:3], s[4:5]
	s_waitcnt lgkmcnt(0)
	v_mad_u64_u32 v[2:3], s[8:9], v64, s21, v[2:3]
	v_lshl_add_u64 v[2:3], v[2:3], 0, v[94:95]
	v_lshl_add_u64 v[64:65], v[2:3], 0, s[12:13]
	v_add_co_u32_e32 v2, vcc, s10, v2
	v_mov_b32_e32 v0, v1
	s_nop 0
	v_addc_co_u32_e32 v3, vcc, 0, v3, vcc
	global_load_dwordx4 v[80:83], v[64:65], off offset:64
	global_load_dwordx4 v[76:79], v[2:3], off offset:1280
	global_load_dwordx4 v[84:87], v[84:85], off
	global_load_dwordx4 v[88:91], v[88:89], off
	v_mov_b32_e32 v2, v1
	v_mov_b32_e32 v3, v1
	v_mov_b64_e32 v[54:55], v[2:3]
	v_mov_b64_e32 v[66:67], v[2:3]
	s_mov_b32 s8, 0
	v_mov_b32_e32 v97, 0xf149f2ca
	v_mov_b32_e32 v96, 0
	v_readlane_b32 s9, v255, 3
	v_mov_b64_e32 v[52:53], v[0:1]
	v_mov_b64_e32 v[64:65], v[0:1]
	s_waitcnt vmcnt(5)
	v_cndmask_b32_e64 v75, v39, 0, s[44:45]
	s_waitcnt vmcnt(4)
	v_cndmask_b32_e64 v71, v43, 0, s[44:45]
	v_cndmask_b32_e64 v70, v42, 0, s[44:45]
	v_cndmask_b32_e64 v69, v41, 0, s[44:45]
	v_cndmask_b32_e64 v68, v40, 0, s[44:45]
	v_cndmask_b32_e64 v74, v38, 0, s[44:45]
	v_cndmask_b32_e64 v73, v37, 0, s[44:45]
	v_cndmask_b32_e64 v72, v36, 0, s[44:45]
	v_mov_b64_e32 v[38:39], v[2:3]
	v_mov_b64_e32 v[42:43], v[2:3]
	v_mov_b64_e32 v[36:37], v[0:1]
	v_mov_b64_e32 v[40:41], v[0:1]
	s_branch .LBB0_1186

; #define LAS __attribute__((address_space(3)))
; __device__ __forceinline__ void kv_gather(KVRegs& r, const bf16_t* Pb, const LAS unsigned short* il, int s, int lane) {
;     const int li = lane & 15, g4 = lane >> 4;
;     const unsigned ra = il[32 * s + li], rb = il[32 * s + 16 + li], rv = il[32 * s + (lane >> 1)];
;     const bf16_t* k0 = Pb + (size_t)ra * NP_ + PC_KC + 8 * g4; const bf16_t* k1 = Pb + (size_t)rb * NP_ + PC_KC + 8 * g4;
;     r.ka[0] = *(const bf16x8*)k0; r.ka[1] = *(const bf16x8*)(k0 + 32); r.kb[0] = *(const bf16x8*)k1; r.kb[1] = *(const bf16x8*)(k1 + 32);
;     const bf16_t* vp = Pb + (size_t)rv * NP_ + PC_VC + (lane & 1) * 32;
; #pragma unroll
;     for (int i = 0; i < 4; ++i) r.v[i] = *(const u32x4*)(vp + 8 * i);
; }
; __device__ __forceinline__ void dsa_unit(int b, int blk, const bf16_t* P, bf16_t* OB, LAS unsigned char* lds, int wave, int tid_in) {
;     ...
;             for (int s = 0; s <= s_hi; s += 2) {
; #pragma unroll
;                 for (int j = 0; j < 2; ++j) {
;                     if (s + j <= s_hi) {
;                         if (s + j + 1 <= s_hi) kv_gather(kv[(j + 1) % 2], Pb, il, s + j + 1, lane);
;                         attn_step(kv[j], bq, vl, lane, CountMask{32 * (s + j), cnt}, m, l, o);
.LBB0_1186:
	s_cmp_ge_i32 s8, s7
	s_cbranch_scc1 .LBB0_1188
	v_add_u32_e32 v0, s9, v109
	v_add_u32_e32 v2, 0x10340, v0
	v_add_u32_e32 v0, 0x10360, v0
	ds_read_u16 v2, v2
	ds_read_u16 v3, v0
	v_add_u32_e32 v0, s9, v108
	v_add_u32_e32 v0, 0x10340, v0
	ds_read_u16 v22, v0
	ds_read_u16 v34, v0 offset:16
	ds_read_u16 v30, v0 offset:32
	ds_read_u16 v26, v0 offset:48
	s_waitcnt lgkmcnt(2)
	v_mul_u32_u24_e32 v0, 0x1c00, v2
	s_waitcnt lgkmcnt(1)
	v_mul_u32_u24_e32 v2, 0x1c00, v3
	v_mov_b32_e32 v3, v1
	v_lshl_add_u64 v[4:5], s[4:5], 0, v[0:1]
	v_mov_b32_e32 v95, v1
	v_lshl_add_u64 v[2:3], s[4:5], 0, v[2:3]
	v_lshl_add_u64 v[4:5], v[4:5], 0, v[94:95]
	s_mov_b64 s[0:1], 0x1500
	v_lshl_add_u64 v[2:3], v[2:3], 0, v[94:95]
	v_lshl_add_u64 v[12:13], v[4:5], 0, s[0:1]
	v_lshl_add_u64 v[16:17], v[2:3], 0, s[0:1]
	s_movk_i32 s0, 0x1000
	v_add_co_u32_e32 v4, vcc, s0, v4
	v_mov_b32_e32 v93, v1
	s_nop 0
	v_addc_co_u32_e32 v5, vcc, 0, v5, vcc
	v_add_co_u32_e32 v2, vcc, s0, v2
	s_mov_b64 s[0:1], 0x1b00
	s_nop 0
	v_addc_co_u32_e32 v3, vcc, 0, v3, vcc
	global_load_dwordx4 v[4:7], v[4:5], off offset:1280
	s_nop 0
	global_load_dwordx4 v[8:11], v[2:3], off offset:1280
	s_nop 0
	global_load_dwordx4 v[12:15], v[12:13], off offset:64
	s_nop 0
	global_load_dwordx4 v[16:19], v[16:17], off offset:64
	v_mov_b64_e32 v[2:3], s[4:5]
	v_lshl_add_u64 v[2:3], v[2:3], 0, v[92:93]
	v_lshl_add_u64 v[2:3], v[2:3], 0, s[0:1]
	s_waitcnt lgkmcnt(0)
	v_mad_u64_u32 v[20:21], s[98:99], v22, s21, v[2:3]
	v_mad_u64_u32 v[24:25], s[98:99], v26, s21, v[2:3]
	v_mad_u64_u32 v[28:29], s[98:99], v30, s21, v[2:3]
	v_mad_u64_u32 v[32:33], s[98:99], v34, s21, v[2:3]
	global_load_dwordx4 v[20:23], v[20:21], off
	global_load_dwordx4 v[24:27], v[24:25], off
	global_load_dwordx4 v[28:31], v[28:29], off
	global_load_dwordx4 v[32:35], v[32:33], off
	s_waitcnt vmcnt(10)
	v_mfma_f32_16x16x32_bf16 v[112:115], v[76:79], v[68:71], 0
	v_subrev_u32_e32 v0, 32, v110
	v_cmp_lt_i32_e32 vcc, v0, v101
	v_add_u32_e32 v0, -16, v110
	v_mfma_f32_16x16x32_bf16 v[116:119], v[60:63], v[68:71], 0
	v_add_u32_e32 v3, v104, v105
	s_waitcnt vmcnt(9)
	ds_write_b128 v3, v[84:87]
	s_waitcnt vmcnt(8)
	ds_write_b128 v3, v[48:51] offset:1024
	ds_write_b128 v3, v[44:47] offset:2048
	s_waitcnt vmcnt(8)
	ds_write_b128 v3, v[88:91] offset:3072
	s_branch .Ldsa3_tailA_1
.LBB0_1188:
	s_waitcnt vmcnt(2)
	v_mfma_f32_16x16x32_bf16 v[112:115], v[76:79], v[68:71], 0
	v_subrev_u32_e32 v0, 32, v110
	v_cmp_lt_i32_e32 vcc, v0, v101
	v_add_u32_e32 v0, -16, v110
	v_mfma_f32_16x16x32_bf16 v[116:119], v[60:63], v[68:71], 0
	v_add_u32_e32 v3, v104, v105
	s_waitcnt vmcnt(1)
	ds_write_b128 v3, v[84:87]
	s_waitcnt vmcnt(0)
	ds_write_b128 v3, v[48:51] offset:1024
	ds_write_b128 v3, v[44:47] offset:2048
	s_waitcnt vmcnt(0)
	ds_write_b128 v3, v[88:91] offset:3072

; #define LAS __attribute__((address_space(3)))
; __device__ __forceinline__ unsigned cvt_pk_bf16(float lo, float hi) { const f32x2 v = {lo, hi}; const bf16x2_t b = __builtin_convertvector(v, bf16x2_t); return __builtin_bit_cast(unsigned, b); }
; __device__ __forceinline__ float fast_exp2(float x) { return __builtin_amdgcn_exp2f(x); }
; #define MFMA16(a, b, c) __builtin_amdgcn_mfma_f32_16x16x32_bf16((a), (b), (c), 0, 0, 0)
; __device__ __forceinline__ s16x4 tr_read(LAS unsigned char* p) { return __builtin_bit_cast(s16x4, __builtin_amdgcn_ds_read_tr16_b64_v4i16((LAS v4i16_t*)p)); }
; template <class MaskF>
; __device__ __forceinline__ void attn_step(const KVRegs& r, const bf16x8 (&bq)[2], LAS unsigned char* vl, int lane, const MaskF mask, float& m, float& l, f32x4 (&o)[4]) {
;     ...
;     float p[8], ps = 0.f;
; #pragma unroll
;     for (int e = 0; e < 8; ++e) { p[e] = fast_exp2(x[e] - mn); ps += p[e]; }
;     l += ps;
;     u32x4 pw; pw.x = cvt_pk_bf16(p[0], p[1]); pw.y = cvt_pk_bf16(p[2], p[3]); pw.z = cvt_pk_bf16(p[4], p[5]); pw.w = cvt_pk_bf16(p[6], p[7]);
;     const bf16x8 pf = __builtin_bit_cast(bf16x8, pw);
;     asm volatile("s_waitcnt lgkmcnt(0)" ::: "memory");
;     LAS unsigned char* rd = vl + (4 * g4 + ((lane & 15) >> 2)) * 128 + (lane & 3) * 8;
; #pragma unroll
;     for (int db = 0; db < 4; ++db) { const s16x4 t0 = tr_read(rd + db * 32), t1 = tr_read(rd + 16 * 128 + db * 32);
;         const bf16x8 vf = (bf16x8){t0[0], t0[1], t0[2], t0[3], t1[0], t1[1], t1[2], t1[3]};
;         o[db] = MFMA16(vf, pf, o[db]); }
;     asm volatile("s_waitcnt lgkmcnt(0)" ::: "memory");
; __device__ __forceinline__ void kv_gather(KVRegs& r, const bf16_t* Pb, const LAS unsigned short* il, int s, int lane) {
;     const int li = lane & 15, g4 = lane >> 4;
;     const unsigned ra = il[32 * s + li], rb = il[32 * s + 16 + li], rv = il[32 * s + (lane >> 1)];
;     const bf16_t* k0 = Pb + (size_t)ra * NP_ + PC_KC + 8 * g4; const bf16_t* k1 = Pb + (size_t)rb * NP_ + PC_KC + 8 * g4;
;     r.ka[0] = *(const bf16x8*)k0; r.ka[1] = *(const bf16x8*)(k0 + 32); r.kb[0] = *(const bf16x8*)k1; r.kb[1] = *(const bf16x8*)(k1 + 32);
;     const bf16_t* vp = Pb + (size_t)rv * NP_ + PC_VC + (lane & 1) * 32;
; #pragma unroll
;     for (int i = 0; i < 4; ++i) r.v[i] = *(const u32x4*)(vp + 8 * i);
; }
.LBB0_1190:
	v_sub_f32_e32 v97, v103, v98
	v_exp_f32_e32 v97, v97
	v_sub_f32_e32 v112, v112, v98
	v_exp_f32_e32 v112, v112
	v_sub_f32_e32 v111, v111, v98
	v_exp_f32_e32 v111, v111
	v_sub_f32_e32 v99, v99, v98
	v_exp_f32_e32 v99, v99
	v_sub_f32_e32 v95, v95, v98
	v_add_f32_e32 v103, 0, v97
	v_exp_f32_e32 v95, v95
	v_sub_f32_e32 v93, v93, v98
	v_add_f32_e32 v103, v112, v103
	v_exp_f32_e32 v93, v93
	v_sub_f32_e32 v2, v2, v98
	v_sub_f32_e32 v0, v0, v98
	v_add_f32_e32 v103, v111, v103
	v_exp_f32_e32 v2, v2
	v_exp_f32_e32 v0, v0
	v_add_f32_e32 v103, v99, v103
	v_add_f32_e32 v103, v95, v103
	v_add_f32_e32 v103, v93, v103
	v_add_f32_e32 v103, v2, v103
	v_cvt_pk_bf16_f32 v115, v2, v0
	s_waitcnt lgkmcnt(0)
	v_add_u32_e32 v2, v106, v107
	ds_read_b64_tr_b16 v[118:119], v2 offset:2048
	ds_read_b64_tr_b16 v[116:117], v2
	ds_read_b64_tr_b16 v[120:121], v2 offset:32
	v_cvt_pk_bf16_f32 v112, v97, v112
	v_cvt_pk_bf16_f32 v113, v111, v99
	v_cvt_pk_bf16_f32 v114, v95, v93
	ds_read_b64_tr_b16 v[122:123], v2 offset:2080
	v_add_f32_e32 v103, v0, v103
	s_waitcnt lgkmcnt(2)
	v_mfma_f32_16x16x32_bf16 v[64:67], v[116:119], v[112:115], v[64:67]
	ds_read_b64_tr_b16 v[116:117], v2 offset:64
	ds_read_b64_tr_b16 v[118:119], v2 offset:2112
	s_add_i32 s0, s8, 1
	v_add_f32_e32 v96, v103, v96
	s_waitcnt lgkmcnt(0)
	v_mfma_f32_16x16x32_bf16 v[40:43], v[116:119], v[112:115], v[40:43]
	ds_read_b64_tr_b16 v[116:117], v2 offset:96
	ds_read_b64_tr_b16 v[118:119], v2 offset:2144
	s_waitcnt lgkmcnt(0)
	s_cmp_ge_i32 s0, s6
	v_mfma_f32_16x16x32_bf16 v[52:55], v[120:123], v[112:115], v[52:55]
	s_waitcnt lgkmcnt(0)
	v_mfma_f32_16x16x32_bf16 v[36:39], v[116:119], v[112:115], v[36:39]
	s_cbranch_scc1 .LBB0_1184
	s_cmp_ge_i32 s0, s7
	s_cbranch_scc1 .LBB0_1193
	v_add_u32_e32 v0, s9, v109
	v_add_u32_e32 v44, 0x10380, v0
	v_add_u32_e32 v0, 0x103a0, v0
	ds_read_u16 v44, v44
	ds_read_u16 v45, v0
	v_add_u32_e32 v0, s9, v108
	v_add_u32_e32 v0, 0x10380, v0
	ds_read_u16 v86, v0
	ds_read_u16 v87, v0 offset:16
	ds_read_u16 v91, v0 offset:32
	ds_read_u16 v90, v0 offset:48
	s_waitcnt lgkmcnt(2)
	v_mul_u32_u24_e32 v0, 0x1c00, v44
	s_waitcnt lgkmcnt(1)
	v_mul_u32_u24_e32 v44, 0x1c00, v45
	v_mov_b32_e32 v45, v1
	v_lshl_add_u64 v[46:47], s[4:5], 0, v[0:1]
	v_mov_b32_e32 v95, v1
	v_lshl_add_u64 v[44:45], s[4:5], 0, v[44:45]
	v_lshl_add_u64 v[46:47], v[46:47], 0, v[94:95]
	s_mov_b64 s[0:1], 0x1500
	v_lshl_add_u64 v[44:45], v[44:45], 0, v[94:95]
	v_lshl_add_u64 v[48:49], v[46:47], 0, s[0:1]
	v_lshl_add_u64 v[50:51], v[44:45], 0, s[0:1]
	s_movk_i32 s0, 0x1000
	v_add_co_u32_e32 v46, vcc, s0, v46
	v_mov_b32_e32 v93, v1
	s_nop 0
	v_addc_co_u32_e32 v47, vcc, 0, v47, vcc
	v_add_co_u32_e32 v44, vcc, s0, v44
	s_nop 1
	v_addc_co_u32_e32 v45, vcc, 0, v45, vcc
	global_load_dwordx4 v[76:79], v[46:47], off offset:1280
	global_load_dwordx4 v[60:63], v[44:45], off offset:1280
	global_load_dwordx4 v[80:83], v[48:49], off offset:64
	global_load_dwordx4 v[56:59], v[50:51], off offset:64
	v_mov_b64_e32 v[46:47], s[4:5]
	v_lshl_add_u64 v[46:47], v[46:47], 0, v[92:93]
	s_mov_b64 s[10:11], 0x1b00
	v_lshl_add_u64 v[46:47], v[46:47], 0, s[10:11]
	s_waitcnt lgkmcnt(0)
	v_mad_u64_u32 v[84:85], s[98:99], v86, s21, v[46:47]
	v_mad_u64_u32 v[88:89], s[98:99], v90, s21, v[46:47]
	v_mad_u64_u32 v[44:45], s[98:99], v91, s21, v[46:47]
	v_mad_u64_u32 v[48:49], s[98:99], v87, s21, v[46:47]
	global_load_dwordx4 v[84:87], v[84:85], off
	global_load_dwordx4 v[88:91], v[88:89], off
	global_load_dwordx4 v[44:47], v[44:45], off
	global_load_dwordx4 v[48:51], v[48:49], off
	s_waitcnt vmcnt(8)
	s_branch .Ldsa3_bodyB_1

; #define LAS __attribute__((address_space(3)))
; __device__ __forceinline__ float fast_exp2(float x) { return __builtin_amdgcn_exp2f(x); }
; __device__ __forceinline__ float xmax16(float v) { const auto r = __builtin_amdgcn_permlane16_swap(__float_as_uint(v), __float_as_uint(v), false, false); return fmaxf(__uint_as_float(r[0]), __uint_as_float(r[1])); }
; __device__ __forceinline__ float xmax32(float v) { const auto r = __builtin_amdgcn_permlane32_swap(__float_as_uint(v), __float_as_uint(v), false, false); return fmaxf(__uint_as_float(r[0]), __uint_as_float(r[1])); }
; #define MFMA16(a, b, c) __builtin_amdgcn_mfma_f32_16x16x32_bf16((a), (b), (c), 0, 0, 0)
; template <class MaskF>
; __device__ __forceinline__ void attn_step(const KVRegs& r, const bf16x8 (&bq)[2], LAS unsigned char* vl, int lane, const MaskF mask, float& m, float& l, f32x4 (&o)[4]) {
;     ...
;     { LAS unsigned char* wp = vl + (lane >> 1) * 128 + (lane & 1) * 64;
; #pragma unroll
;       for (int i = 0; i < 4; ++i) *(LAS u32x4*)(wp + 16 * i) = r.v[i]; }
;     f32x4 sa = (f32x4){0.f, 0.f, 0.f, 0.f}, sb = (f32x4){0.f, 0.f, 0.f, 0.f};
;     sa = MFMA16(r.ka[0], bq[0], sa); sa = MFMA16(r.ka[1], bq[1], sa);
;     sb = MFMA16(r.kb[0], bq[0], sb); sb = MFMA16(r.kb[1], bq[1], sb);
;     float x[8];
; #pragma unroll
;     for (int e = 0; e < 4; ++e) { x[e] = mask(4 * g4 + e, sa[e]); x[4 + e] = mask(16 + 4 * g4 + e, sb[e]); }
;     float tm = fmaxf(fmaxf(fmaxf(x[0], x[1]), fmaxf(x[2], x[3])), fmaxf(fmaxf(x[4], x[5]), fmaxf(x[6], x[7])));
;     tm = xmax32(xmax16(tm));
;     const float mn = fmaxf(m, tm);
;     if (__ballot(mn > m)) { const float al = fast_exp2(m - mn); l *= al;
; #pragma unroll
;         for (int db = 0; db < 4; ++db) o[db] = o[db] * al; }
.Ldsa3_bodyB_1:
	v_mfma_f32_16x16x32_bf16 v[112:115], v[4:7], v[68:71], 0
	v_cmp_lt_i32_e32 vcc, v110, v101
	v_add_u32_e32 v0, 16, v110
	ds_write_b128 v3, v[20:23]
	v_mfma_f32_16x16x32_bf16 v[116:119], v[8:11], v[68:71], 0
	ds_write_b128 v3, v[32:35] offset:1024
	ds_write_b128 v3, v[28:31] offset:2048
	ds_write_b128 v3, v[24:27] offset:3072
	v_mfma_f32_16x16x32_bf16 v[112:115], v[12:15], v[72:75], v[112:115]
	v_mfma_f32_16x16x32_bf16 v[116:119], v[16:19], v[72:75], v[116:119]
	s_nop 6
	v_cndmask_b32_e32 v103, v233, v112, vcc
	v_cmp_lt_i32_e32 vcc, v0, v101
	v_add_u32_e32 v0, 1, v110
	s_nop 0
	v_cndmask_b32_e32 v95, v233, v116, vcc
	v_cmp_lt_i32_e32 vcc, v0, v101
	v_add_u32_e32 v0, 17, v110
	s_nop 0
	v_cndmask_b32_e32 v112, v233, v113, vcc
	v_cmp_lt_i32_e32 vcc, v0, v101
	v_add_u32_e32 v0, 2, v110
	v_max_f32_e32 v97, v112, v112
	v_cndmask_b32_e32 v93, v233, v117, vcc
	v_cmp_lt_i32_e32 vcc, v0, v101
	v_add_u32_e32 v0, 18, v110
	v_max_f32_e32 v113, v103, v103
	v_cndmask_b32_e32 v111, v233, v114, vcc
	v_cmp_lt_i32_e32 vcc, v0, v101
	v_add_u32_e32 v0, 3, v110
	v_max_f32_e32 v97, v113, v97
	v_cndmask_b32_e32 v3, v233, v118, vcc
	v_cmp_lt_i32_e32 vcc, v0, v101
	v_add_u32_e32 v0, 19, v110
	v_max_f32_e32 v114, v111, v111
	v_cndmask_b32_e32 v99, v233, v115, vcc
	v_cmp_lt_i32_e32 vcc, v0, v101
	v_max_f32_e32 v113, v99, v99
	v_max_f32_e32 v113, v114, v113
	v_cndmask_b32_e32 v0, v233, v119, vcc
	v_max_f32_e32 v114, v0, v0
	v_max_f32_e32 v115, v3, v3
	v_max_f32_e32 v114, v115, v114
	v_max3_f32 v114, v95, v93, v114
	v_max3_f32 v97, v97, v113, v114
	v_mov_b32_e32 v113, v97
	s_nop 1
	v_permlane16_swap_b32_e32 v97, v113
	v_max_f32_e32 v113, v113, v113
	v_max_f32_e32 v97, v97, v97
	v_max_f32_e32 v97, v97, v113
	v_mov_b32_e32 v113, v97
	s_nop 1
	v_permlane32_swap_b32_e32 v97, v113
	v_max3_f32 v97, v98, v97, v113
	v_cmp_gt_f32_e32 vcc, v97, v98
	s_cbranch_vccz .LBB0_1195
	v_sub_f32_e32 v98, v98, v97
	v_exp_f32_e32 v98, v98
	s_nop 0
	v_mul_f32_e32 v96, v96, v98
	v_pk_mul_f32 v[66:67], v[66:67], v[98:99] op_sel_hi:[1,0]
	v_pk_mul_f32 v[64:65], v[64:65], v[98:99] op_sel_hi:[1,0]
	v_pk_mul_f32 v[54:55], v[54:55], v[98:99] op_sel_hi:[1,0]
	v_pk_mul_f32 v[52:53], v[52:53], v[98:99] op_sel_hi:[1,0]
	v_pk_mul_f32 v[42:43], v[42:43], v[98:99] op_sel_hi:[1,0]
	v_pk_mul_f32 v[40:41], v[40:41], v[98:99] op_sel_hi:[1,0]
	v_pk_mul_f32 v[38:39], v[38:39], v[98:99] op_sel_hi:[1,0]
	v_pk_mul_f32 v[36:37], v[36:37], v[98:99] op_sel_hi:[1,0]

; __device__ __forceinline__ unsigned xb_add(unsigned* p, unsigned v) { return __hip_atomic_fetch_add(p, v, __ATOMIC_RELAXED, __HIP_MEMORY_SCOPE_AGENT); }
; __device__ __forceinline__ void xcd_barrier(const XcdBarrier& b) {
;     ...
;     if (threadIdx.x == 0) {
;         unsigned* bar = b.bar;
;         __builtin_amdgcn_s_waitcnt(0);
;         unsigned nloc = b.st[0], nx = b.st[1];
;         if (nloc == 0u) { xcd_barrier_complete(bar, b.x, nloc, nx); b.st[0] = nloc; b.st[1] = nx; }
;         const unsigned old = xb_add(&bar[XB_XSUB(b.x)], 1u);
;         const unsigned gen = old / nloc;
;         if (old + 1u == (gen + 1u) * nloc) {
.LBB0_1314:
	s_mov_b64 s[8:9], exec
	v_mbcnt_lo_u32_b32 v0, s8, 0
	v_mbcnt_hi_u32_b32 v0, s9, v0
	v_cmp_eq_u32_e32 vcc, 0, v0
	s_and_saveexec_b64 s[6:7], vcc
	s_cbranch_execz .LBB0_1316
	s_bcnt1_i32_b64 s1, s[8:9]
	buffer_wbl2 sc1
	v_readlane_b32 s2, v252, 1
	v_mov_b32_e32 v4, s1
	v_readlane_b32 s3, v252, 2
	s_nop 4
	global_atomic_add v4, v1, v4, s[2:3] sc0
